# PROJ GEMM 45->44 column tiles; 16 beta/decay columns via a skinny MFMA block on all WGs
# speedup vs baseline: 1.0166x; 1.0166x over previous
; __device__ __forceinline__ void gemm_range(const Args& a, LAS unsigned char* lds, int lo, int hi, int first, int last, int G, int bx, int NGW, const XcdBarrier& xbar) {
;     ...
;             case P_PROJ: g = {hb, (const bf16_t*)(ws + WS_WIN), TOK, NIN, DM, DM}; E.mode = pg8::E_SCALE; E.ssq = ssqx + TOK; E.outb = proj; E.ldo = NIN; E.halo = (bf16_t*)(ws + WS_HALO); E.baf = (float*)(ws + WS_BAF); break;
;             case P_BRANCH:
;                 if (gi == 0) { g = {proj, (const bf16_t*)(ws + WS_WBA), TOK, DM, 1024, NIN}; E.mode = pg8::E_BR1; }
;                 else { g = {proj + C_Z, (const bf16_t*)(ws + WS_WBD), TOK, DM, 1024, NIN}; E.mode = pg8::E_BR2; E.gate = proj + C_GB; }
;                 E.outb = proj + C_GA; E.ldo = NIN; break;
;             case P_WOUT: g = {proj + C_GA, (const bf16_t*)(ws + WS_WOUT), TOK, DM, DM, NIN}; E.mode = pg8::E_RESID; E.hinb = hb; E.hout = nullptr; E.alpha = 1.f; E.ssq_out = ssqx + 2 * TOK; E.hb = hb; break;
;             case P_XQ:
;                 if (gi == 0) { g = {hb, (const bf16_t*)(ws + WS_WQ), TOK, 512, DM, DM}; E.ssq = ssqx + 2 * TOK; E.outb = (bf16_t*)(ws + WS_QX); E.ldo = 512; }
;                 else { g = {(const bf16_t*)(ws + WS_MEMB), (const bf16_t*)(ws + WS_WKV), 1024, 1024, DM, DM}; E.ssqf = ctl + CT_SSQM; E.outb = (bf16_t*)(ws + WS_KVX); E.ldo = 1024; rot = 128; }
;                 E.mode = pg8::E_SCALE; break;
;             case P_XO: g = {(const bf16_t*)(ws + WS_OX), (const bf16_t*)(ws + WS_WO), TOK, DM, 512, 512}; E.mode = pg8::E_RESID; E.hinb = hb; E.hout = nullptr; E.alpha = 1.f; E.ssq_out = ssqx + 3 * TOK; E.hb = hb; break;
;             case P_GU2: g = {hb, (const bf16_t*)(ws + WS_WGU), TOK, NGU, DM, DM}; E.mode = pg8::E_GU; E.ssq = ssqx + 3 * TOK; E.outb = hff; E.ldo = FF; break;
;             default: g = {hff, (const bf16_t*)(ws + WS_WD), TOK, DM, FF, FF}; E.mode = pg8::E_RESID; E.hinb = hb; E.hout = nullptr; E.alpha = 0.5f; E.ssq_out = ssqx + 4 * TOK; E.hb = hb; break;
;             }
;             if (a.probe && E.mode == pg8::E_RESID) { if (E.hout) E.hout = (float*)(ws + 389 * MiB); E.ssq_out = (u64*)(ws + 524 * MiB); if (E.hb) E.hb = (bf16_t*)(ws + 38 * MiB); }
;             pg8::StaticOrder S; S.init(g.M, g.N, G, (bx + rot) % G);
;             __syncthreads();
.LBB0_383:
	s_mov_b64 s[26:27], 0
	s_andn2_b64 vcc, exec, s[28:29]
	s_mov_b64 s[22:23], 0
	s_cbranch_vccnz .LBB0_385
	s_add_u32 s22, s0, 0x1e80000
	s_addc_u32 s23, s1, 0
	s_add_u32 s26, s0, 0x1a00000
	s_addc_u32 s27, s1, 0
	s_add_u32 s92, s0, 0x6600000
	s_addc_u32 s93, s1, 0
	s_mov_b64 s[12:13], 0
	s_mov_b32 s2, 0
	s_movk_i32 s39, 0x2d00
	s_mov_b32 s41, 2
	s_movk_i32 s35, 0x800
	s_mov_b32 s3, 44
	s_mov_b64 s[94:95], s[4:5]
	s_movk_i32 s40, 0x800
	s_mov_b64 s[20:21], s[90:91]
	s_mov_b64 s[16:17], s[6:7]
	s_mov_b64 s[18:19], 0
	s_mov_b64 s[24:25], 0
	s_andn2_b64 vcc, exec, s[14:15]
	s_cbranch_vccnz .LBB0_390
	s_branch .LBB0_386

; __device__ __forceinline__ float ssq_val(u64 v) { return (float)v * (1.f / 4294967296.f); }
; __device__ __forceinline__ unsigned pk2(float lo, float hi) { const f32x2 v = {lo, hi}; return __builtin_bit_cast(unsigned, __builtin_convertvector(v, hbf2)); }
;     __device__ __forceinline__ void operator()(const f32x4 (&acc)[2][2][4][2], const Unit& u, int wr, int wc, int fr, int fq, LAS f32x4* rsc, bool reuse) const {
;     ...
;                     for (int m = 0; m < 4; ++m) rs[ai][m] = ssqf ? ssqf[row0 + ai * HALF + m * 16] : ssq_val(ssq[row0 + ai * HALF + m * 16]);
; #pragma unroll
;                 for (int ai = 0; ai < 2; ++ai)
; #pragma unroll
;                     for (int m = 0; m < 4; ++m) rs[ai][m] = __builtin_amdgcn_rsqf(rs[ai][m] * (1.f / DM) + EPS);
;     ...
;                             const f32x4 v0 = acc[ai][bj][m][0] * r, v1 = acc[ai][bj][m][1] * r;
;                             u32x4 w; w.x = pk2(v0[0], v0[1]); w.y = pk2(v0[2], v0[3]); w.z = pk2(v1[0], v1[1]); w.w = pk2(v1[2], v1[3]);
;                             if (is_ba) { if (bj == 0 && cl < 16) { *(f32x4*)(baf + (size_t)row * 16 + cl) = v0; *(f32x4*)(baf + (size_t)row * 16 + cl + 4) = v1; } }
.LBB0_681:
	s_cmp_lg_u32 s38, 3
	s_cbranch_scc1 .Lsk_done
	v_readlane_b32 s2, v253, 4
	v_readlane_b32 s3, v253, 5
	v_readlane_b32 s4, v253, 13
.Lsk_loop:
	v_and_b32_e32 v16, 63, v205
	v_lshrrev_b32_e32 v17, 6, v205
	v_and_b32_e32 v18, 15, v16
	v_lshrrev_b32_e32 v19, 4, v16
	v_and_b32_e32 v20, 3, v17
	v_lshrrev_b32_e32 v21, 2, v17
	s_lshl_b32 s5, s4, 6
	v_lshl_add_u32 v22, v20, 4, v18
	v_add_u32_e32 v22, s5, v22
	v_lshlrev_b32_e32 v23, 11, v21
	v_lshl_add_u32 v23, v19, 4, v23
	v_lshl_add_u32 v24, v22, 12, v23
	v_add_u32_e32 v24, 0x2600000, v24
	v_lshl_add_u32 v25, v18, 12, v23
	v_add_u32_e32 v25, 0x9200000, v25
	v_lshlrev_b32_e32 v28, 3, v22
	v_add_u32_e32 v28, 0x20000, v28
	v_readfirstlane_b32 s6, v21
	v_lshl_add_u32 v29, v20, 10, 0
	v_lshl_add_u32 v29, v16, 4, v29
	v_lshlrev_b32_e32 v30, 6, v22
	v_lshl_add_u32 v30, v19, 4, v30
	v_add_u32_e32 v30, 0x1e80000, v30
	s_nop 4
	global_load_dwordx2 v[26:27], v28, s[2:3]
	global_load_dwordx4 v[144:147], v24, s[2:3] offset:0
	global_load_dwordx4 v[148:151], v24, s[2:3] offset:64
	global_load_dwordx4 v[152:155], v24, s[2:3] offset:128
	global_load_dwordx4 v[156:159], v24, s[2:3] offset:192
	global_load_dwordx4 v[160:163], v25, s[2:3] offset:0
	global_load_dwordx4 v[164:167], v25, s[2:3] offset:64
	global_load_dwordx4 v[168:171], v25, s[2:3] offset:128
	global_load_dwordx4 v[172:175], v25, s[2:3] offset:192
	global_load_dwordx4 v[176:179], v24, s[2:3] offset:256
	global_load_dwordx4 v[180:183], v24, s[2:3] offset:320
	global_load_dwordx4 v[184:187], v24, s[2:3] offset:384
	global_load_dwordx4 v[188:191], v24, s[2:3] offset:448
	global_load_dwordx4 v[192:195], v25, s[2:3] offset:256
	global_load_dwordx4 v[196:199], v25, s[2:3] offset:320
	global_load_dwordx4 v[200:203], v25, s[2:3] offset:384
	global_load_dwordx4 v[76:79], v25, s[2:3] offset:448
	global_load_dwordx4 v[80:83], v24, s[2:3] offset:512
	global_load_dwordx4 v[84:87], v24, s[2:3] offset:576
	global_load_dwordx4 v[88:91], v24, s[2:3] offset:640
	global_load_dwordx4 v[92:95], v24, s[2:3] offset:704
	global_load_dwordx4 v[96:99], v25, s[2:3] offset:512
	global_load_dwordx4 v[100:103], v25, s[2:3] offset:576
	global_load_dwordx4 v[104:107], v25, s[2:3] offset:640
	global_load_dwordx4 v[108:111], v25, s[2:3] offset:704
	s_waitcnt vmcnt(16)
	v_mfma_f32_16x16x32_bf16 v[8:11], v[160:163], v[144:147], 0
	v_mfma_f32_16x16x32_bf16 v[8:11], v[164:167], v[148:151], v[8:11]
	v_mfma_f32_16x16x32_bf16 v[8:11], v[168:171], v[152:155], v[8:11]
	v_mfma_f32_16x16x32_bf16 v[8:11], v[172:175], v[156:159], v[8:11]
	global_load_dwordx4 v[144:147], v24, s[2:3] offset:768
	global_load_dwordx4 v[148:151], v24, s[2:3] offset:832
	global_load_dwordx4 v[152:155], v24, s[2:3] offset:896
	global_load_dwordx4 v[156:159], v24, s[2:3] offset:960
	global_load_dwordx4 v[160:163], v25, s[2:3] offset:768
	global_load_dwordx4 v[164:167], v25, s[2:3] offset:832
	global_load_dwordx4 v[168:171], v25, s[2:3] offset:896
	global_load_dwordx4 v[172:175], v25, s[2:3] offset:960
	s_waitcnt vmcnt(16)
	v_mfma_f32_16x16x32_bf16 v[8:11], v[192:195], v[176:179], v[8:11]
	v_mfma_f32_16x16x32_bf16 v[8:11], v[196:199], v[180:183], v[8:11]
	v_mfma_f32_16x16x32_bf16 v[8:11], v[200:203], v[184:187], v[8:11]
	v_mfma_f32_16x16x32_bf16 v[8:11], v[76:79], v[188:191], v[8:11]
	global_load_dwordx4 v[176:179], v24, s[2:3] offset:1024
	global_load_dwordx4 v[180:183], v24, s[2:3] offset:1088
	global_load_dwordx4 v[184:187], v24, s[2:3] offset:1152
	global_load_dwordx4 v[188:191], v24, s[2:3] offset:1216
	global_load_dwordx4 v[192:195], v25, s[2:3] offset:1024
	global_load_dwordx4 v[196:199], v25, s[2:3] offset:1088
	global_load_dwordx4 v[200:203], v25, s[2:3] offset:1152
	global_load_dwordx4 v[76:79], v25, s[2:3] offset:1216
	s_waitcnt vmcnt(16)
; __device__ __forceinline__ float ssq_val(u64 v) { return (float)v * (1.f / 4294967296.f); }
; __device__ __forceinline__ unsigned pk2(float lo, float hi) { const f32x2 v = {lo, hi}; return __builtin_bit_cast(unsigned, __builtin_convertvector(v, hbf2)); }
;     __device__ __forceinline__ void operator()(const f32x4 (&acc)[2][2][4][2], const Unit& u, int wr, int wc, int fr, int fq, LAS f32x4* rsc, bool reuse) const {
;     ...
;                     for (int m = 0; m < 4; ++m) rs[ai][m] = ssqf ? ssqf[row0 + ai * HALF + m * 16] : ssq_val(ssq[row0 + ai * HALF + m * 16]);
; #pragma unroll
;                 for (int ai = 0; ai < 2; ++ai)
; #pragma unroll
;                     for (int m = 0; m < 4; ++m) rs[ai][m] = __builtin_amdgcn_rsqf(rs[ai][m] * (1.f / DM) + EPS);
;     ...
;                             const f32x4 v0 = acc[ai][bj][m][0] * r, v1 = acc[ai][bj][m][1] * r;
;                             u32x4 w; w.x = pk2(v0[0], v0[1]); w.y = pk2(v0[2], v0[3]); w.z = pk2(v1[0], v1[1]); w.w = pk2(v1[2], v1[3]);
;                             if (is_ba) { if (bj == 0 && cl < 16) { *(f32x4*)(baf + (size_t)row * 16 + cl) = v0; *(f32x4*)(baf + (size_t)row * 16 + cl + 4) = v1; } }
	v_mfma_f32_16x16x32_bf16 v[8:11], v[96:99], v[80:83], v[8:11]
	v_mfma_f32_16x16x32_bf16 v[8:11], v[100:103], v[84:87], v[8:11]
	v_mfma_f32_16x16x32_bf16 v[8:11], v[104:107], v[88:91], v[8:11]
	v_mfma_f32_16x16x32_bf16 v[8:11], v[108:111], v[92:95], v[8:11]
	global_load_dwordx4 v[80:83], v24, s[2:3] offset:1280
	global_load_dwordx4 v[84:87], v24, s[2:3] offset:1344
	global_load_dwordx4 v[88:91], v24, s[2:3] offset:1408
	global_load_dwordx4 v[92:95], v24, s[2:3] offset:1472
	global_load_dwordx4 v[96:99], v25, s[2:3] offset:1280
	global_load_dwordx4 v[100:103], v25, s[2:3] offset:1344
	global_load_dwordx4 v[104:107], v25, s[2:3] offset:1408
	global_load_dwordx4 v[108:111], v25, s[2:3] offset:1472
	s_waitcnt vmcnt(16)
	v_mfma_f32_16x16x32_bf16 v[8:11], v[160:163], v[144:147], v[8:11]
	v_mfma_f32_16x16x32_bf16 v[8:11], v[164:167], v[148:151], v[8:11]
	v_mfma_f32_16x16x32_bf16 v[8:11], v[168:171], v[152:155], v[8:11]
	v_mfma_f32_16x16x32_bf16 v[8:11], v[172:175], v[156:159], v[8:11]
	global_load_dwordx4 v[144:147], v24, s[2:3] offset:1536
	global_load_dwordx4 v[148:151], v24, s[2:3] offset:1600
	global_load_dwordx4 v[152:155], v24, s[2:3] offset:1664
	global_load_dwordx4 v[156:159], v24, s[2:3] offset:1728
	global_load_dwordx4 v[160:163], v25, s[2:3] offset:1536
	global_load_dwordx4 v[164:167], v25, s[2:3] offset:1600
	global_load_dwordx4 v[168:171], v25, s[2:3] offset:1664
	global_load_dwordx4 v[172:175], v25, s[2:3] offset:1728
	s_waitcnt vmcnt(16)
	v_mfma_f32_16x16x32_bf16 v[8:11], v[192:195], v[176:179], v[8:11]
	v_mfma_f32_16x16x32_bf16 v[8:11], v[196:199], v[180:183], v[8:11]
	v_mfma_f32_16x16x32_bf16 v[8:11], v[200:203], v[184:187], v[8:11]
	v_mfma_f32_16x16x32_bf16 v[8:11], v[76:79], v[188:191], v[8:11]
	global_load_dwordx4 v[176:179], v24, s[2:3] offset:1792
	global_load_dwordx4 v[180:183], v24, s[2:3] offset:1856
	global_load_dwordx4 v[184:187], v24, s[2:3] offset:1920
	global_load_dwordx4 v[188:191], v24, s[2:3] offset:1984
	global_load_dwordx4 v[192:195], v25, s[2:3] offset:1792
	global_load_dwordx4 v[196:199], v25, s[2:3] offset:1856
	global_load_dwordx4 v[200:203], v25, s[2:3] offset:1920
	global_load_dwordx4 v[76:79], v25, s[2:3] offset:1984
	s_waitcnt vmcnt(16)
	v_mfma_f32_16x16x32_bf16 v[8:11], v[96:99], v[80:83], v[8:11]
	v_mfma_f32_16x16x32_bf16 v[8:11], v[100:103], v[84:87], v[8:11]
	v_mfma_f32_16x16x32_bf16 v[8:11], v[104:107], v[88:91], v[8:11]
	v_mfma_f32_16x16x32_bf16 v[8:11], v[108:111], v[92:95], v[8:11]
	s_waitcnt vmcnt(8)
	v_mfma_f32_16x16x32_bf16 v[8:11], v[160:163], v[144:147], v[8:11]
	v_mfma_f32_16x16x32_bf16 v[8:11], v[164:167], v[148:151], v[8:11]
	v_mfma_f32_16x16x32_bf16 v[8:11], v[168:171], v[152:155], v[8:11]
	v_mfma_f32_16x16x32_bf16 v[8:11], v[172:175], v[156:159], v[8:11]
	s_waitcnt vmcnt(0)
	v_mfma_f32_16x16x32_bf16 v[8:11], v[192:195], v[176:179], v[8:11]
	v_mfma_f32_16x16x32_bf16 v[8:11], v[196:199], v[180:183], v[8:11]
	v_mfma_f32_16x16x32_bf16 v[8:11], v[200:203], v[184:187], v[8:11]
	v_mfma_f32_16x16x32_bf16 v[8:11], v[76:79], v[188:191], v[8:11]
	v_cvt_f32_u32_e32 v31, v27
	v_cvt_f32_u32_e32 v12, v26
	v_mov_b32_e32 v13, 0x2f800000
	v_fmac_f32_e32 v31, v12, v13
	v_mov_b32_e32 v13, 0x358637bd
	v_fmamk_f32 v31, v31, 0x3a000000, v13
	v_rsq_f32_e32 v31, v31
	s_nop 7
	s_nop 1
	s_cmp_eq_u32 s6, 0
	s_cbranch_scc1 .Lsk_lo
	ds_write_b128 v29, v[8:11]
	s_waitcnt lgkmcnt(0)
	s_barrier
	s_branch .Lsk_tail
.Lsk_lo:
	s_barrier
	ds_read_b128 v[12:15], v29
	s_waitcnt lgkmcnt(0)
	v_add_f32_e32 v8, v8, v12
	v_add_f32_e32 v9, v9, v13
	v_add_f32_e32 v10, v10, v14
	v_add_f32_e32 v11, v11, v15
	v_mul_f32_e32 v8, v8, v31
	v_mul_f32_e32 v9, v9, v31
	v_mul_f32_e32 v10, v10, v31
	v_mul_f32_e32 v11, v11, v31
	global_store_dwordx4 v30, v[8:11], s[2:3]
.Lsk_tail:
	s_add_i32 s4, s4, s69
	s_cmpk_lt_u32 s4, 0x100
	s_cbranch_scc0 .Lsk_done
	s_barrier
	s_branch .Lsk_loop
